# plus MLA ds_read hoisting (4 in flight) and ssd_a x-conv ushort load hoisting
# speedup vs baseline: 1.0387x; 1.0387x over previous
.LBB0_241:
	v_readlane_b32 s2, v253, 7
	s_add_i32 s58, s81, -2
	v_readlane_b32 s3, v253, 8
	s_mov_b32 s49, s3
	s_min_i32 s48, s58, s78
	s_lshl_b64 s[2:3], s[48:49], 17
	v_lshl_add_u64 v[2:3], v[200:201], 0, s[2:3]
	s_mov_b32 s2, 0x10000
	v_add_co_u32_e32 v4, vcc, s2, v2
	s_lshl_b64 s[2:3], s[48:49], 13
	s_nop 0
	v_addc_co_u32_e32 v5, vcc, 0, v3, vcc
	global_load_dwordx4 v[176:179], v[2:3], off
	global_load_dwordx4 v[180:183], v[4:5], off
	v_lshl_add_u64 v[2:3], v[202:203], 0, s[2:3]
	s_mov_b32 s3, s49
	v_writelane_b32 v253, s2, 7
	global_load_dwordx4 v[184:187], v[2:3], off
	s_add_i32 s62, s81, -5
	v_writelane_b32 v253, s3, 8
	s_lshl_b64 s[2:3], s[48:49], 8
	v_lshl_add_u64 v[2:3], v[204:205], 0, s[2:3]
	v_add_co_u32_e32 v4, vcc, 0x82000, v2
	s_xor_b64 s[64:65], s[8:9], -1
	s_nop 0
	v_addc_co_u32_e32 v5, vcc, 0, v3, vcc
	global_load_dwordx4 v[192:195], v[2:3], off
	global_load_dwordx4 v[188:191], v[4:5], off
	v_cmp_le_i32_e32 vcc, s62, v199
	v_add_u32_e32 v233, s81, v231
	s_and_b32 s59, s62, 1
	s_and_b64 s[2:3], s[64:65], vcc
	s_and_saveexec_b64 s[66:67], s[2:3]
	s_cbranch_execz .LBB0_259
	s_mul_i32 s2, s59, 0xac00
	v_or_b32_e32 v234, s2, v196
	v_add_u32_e32 v235, v234, v229
	ds_read_b128 v[2:5], v235
	ds_read_b128 v[6:9], v235 offset:32
	v_cmp_ge_i32_e32 vcc, s62, v199
	v_mov_b32_e32 v62, v0
	v_mov_b32_e32 v63, v0
	s_waitcnt lgkmcnt(1)
	v_mfma_f32_32x32x16_bf16 v[80:95], v[2:5], v[112:115], 0
	v_cndmask_b32_e32 v1, 3, v228, vcc
	v_mov_b32_e32 v48, 0xf149f2ca
	v_mov_b32_e32 v49, v0
	v_mov_b32_e32 v50, v0
	v_mov_b32_e32 v51, v0
	v_mov_b32_e32 v52, v0
	v_mov_b32_e32 v53, v0
	s_waitcnt lgkmcnt(0)
	v_mfma_f32_32x32x16_bf16 v[80:95], v[6:9], v[116:119], v[80:95]
	ds_read_b128 v[2:5], v235 offset:64
	ds_read_b128 v[6:9], v235 offset:96
	v_mov_b32_e32 v54, v0
	v_mov_b32_e32 v55, v0
	v_mov_b32_e32 v56, v0
	v_mov_b32_e32 v57, v0
	v_mov_b32_e32 v58, v0
	v_mov_b32_e32 v59, v0
	s_waitcnt lgkmcnt(1)
	v_mfma_f32_32x32x16_bf16 v[80:95], v[2:5], v[120:123], v[80:95]
	ds_read_b128 v[2:5], v235 offset:128
	v_mov_b32_e32 v60, v0
	v_mov_b32_e32 v61, v0
	v_mov_b64_e32 v[110:111], v[62:63]
	v_cmp_ne_u32_e64 s[52:53], 0, v1
	v_mov_b64_e32 v[108:109], v[60:61]
	v_mov_b64_e32 v[106:107], v[58:59]
	s_waitcnt lgkmcnt(1)
	v_mfma_f32_32x32x16_bf16 v[80:95], v[6:9], v[124:127], v[80:95]
	ds_read_b128 v[6:9], v235 offset:160
	v_mov_b64_e32 v[104:105], v[56:57]
	v_mov_b64_e32 v[102:103], v[54:55]
	v_mov_b64_e32 v[100:101], v[52:53]
	v_mov_b64_e32 v[98:99], v[50:51]
	v_mov_b64_e32 v[96:97], v[48:49]
	s_waitcnt lgkmcnt(1)
	v_mfma_f32_32x32x16_bf16 v[80:95], v[2:5], v[128:131], v[80:95]
	s_waitcnt lgkmcnt(0)
	v_mfma_f32_32x32x16_bf16 v[80:95], v[6:9], v[132:135], v[80:95]
	s_and_saveexec_b64 s[48:49], s[52:53]
	s_cbranch_execz .LBB0_244
	ds_read_b128 v[2:5], v235 offset:6656
	ds_read_b128 v[212:215], v235 offset:6688
	ds_read_b128 v[216:219], v235 offset:6720
	ds_read_b128 v[220:223], v235 offset:6752
	s_waitcnt lgkmcnt(3)
	v_mfma_f32_32x32x16_bf16 v[96:111], v[2:5], v[112:115], 0
	ds_read_b128 v[2:5], v235 offset:6784
	s_waitcnt lgkmcnt(3)
	v_mfma_f32_32x32x16_bf16 v[96:111], v[212:215], v[116:119], v[96:111]
	ds_read_b128 v[212:215], v235 offset:6816
	s_waitcnt lgkmcnt(3)
	v_mfma_f32_32x32x16_bf16 v[96:111], v[216:219], v[120:123], v[96:111]
	s_waitcnt lgkmcnt(2)
	v_mfma_f32_32x32x16_bf16 v[96:111], v[220:223], v[124:127], v[96:111]
	s_waitcnt lgkmcnt(1)
	v_mfma_f32_32x32x16_bf16 v[96:111], v[2:5], v[128:131], v[96:111]
	s_waitcnt lgkmcnt(0)
	v_mfma_f32_32x32x16_bf16 v[96:111], v[212:215], v[132:135], v[96:111]
.LBB0_244:
	s_or_b64 exec, exec, s[48:49]
	v_cmp_lt_u32_e64 s[50:51], 1, v1
	s_and_saveexec_b64 s[48:49], s[50:51]
	s_cbranch_execz .LBB0_246
	ds_read_b128 v[2:5], v235 offset:13312
	ds_read_b128 v[212:215], v235 offset:13344
	ds_read_b128 v[216:219], v235 offset:13376
	ds_read_b128 v[220:223], v235 offset:13408
	s_waitcnt lgkmcnt(3)
	v_mfma_f32_32x32x16_bf16 v[48:63], v[2:5], v[112:115], 0
	ds_read_b128 v[2:5], v235 offset:13440
	s_waitcnt lgkmcnt(3)
	v_mfma_f32_32x32x16_bf16 v[48:63], v[212:215], v[116:119], v[48:63]
	ds_read_b128 v[212:215], v235 offset:13472
	s_waitcnt lgkmcnt(3)
	v_mfma_f32_32x32x16_bf16 v[48:63], v[216:219], v[120:123], v[48:63]
	s_waitcnt lgkmcnt(2)
	v_mfma_f32_32x32x16_bf16 v[48:63], v[220:223], v[124:127], v[48:63]
	s_waitcnt lgkmcnt(1)
	v_mfma_f32_32x32x16_bf16 v[48:63], v[2:5], v[128:131], v[48:63]
	s_waitcnt lgkmcnt(0)
	v_mfma_f32_32x32x16_bf16 v[48:63], v[212:215], v[132:135], v[48:63]
.LBB0_246:
	s_or_b64 exec, exec, s[48:49]
	v_mov_b32_e32 v14, v0
	v_mov_b32_e32 v15, v0
	v_cmp_eq_u32_e64 s[48:49], 3, v1
	v_mov_b32_e32 v1, v0
	v_mov_b32_e32 v2, v0
	v_mov_b32_e32 v3, v0
	v_mov_b32_e32 v4, v0
	v_mov_b32_e32 v5, v0
	v_mov_b32_e32 v6, v0
	v_mov_b32_e32 v7, v0
	v_mov_b32_e32 v8, v0
	v_mov_b32_e32 v9, v0
	v_mov_b32_e32 v10, v0
	v_mov_b32_e32 v11, v0
	v_mov_b32_e32 v12, v0
	v_mov_b32_e32 v13, v0
	v_mov_b64_e32 v[78:79], v[14:15]
	v_mov_b64_e32 v[76:77], v[12:13]
	v_mov_b64_e32 v[74:75], v[10:11]
	v_mov_b64_e32 v[72:73], v[8:9]
	v_mov_b64_e32 v[70:71], v[6:7]
	v_mov_b64_e32 v[68:69], v[4:5]
	v_mov_b64_e32 v[66:67], v[2:3]
	v_mov_b64_e32 v[64:65], v[0:1]
	s_and_saveexec_b64 s[56:57], s[48:49]
	s_cbranch_execz .LBB0_248
	ds_read_b128 v[2:5], v235 offset:19968
	ds_read_b128 v[212:215], v235 offset:20000
	ds_read_b128 v[216:219], v235 offset:20032
	ds_read_b128 v[220:223], v235 offset:20064
	s_waitcnt lgkmcnt(3)
	v_mfma_f32_32x32x16_bf16 v[64:79], v[2:5], v[112:115], 0
	ds_read_b128 v[2:5], v235 offset:20096
	s_waitcnt lgkmcnt(3)
	v_mfma_f32_32x32x16_bf16 v[64:79], v[212:215], v[116:119], v[64:79]
	ds_read_b128 v[212:215], v235 offset:20128
	s_waitcnt lgkmcnt(3)
	v_mfma_f32_32x32x16_bf16 v[64:79], v[216:219], v[120:123], v[64:79]
	s_waitcnt lgkmcnt(2)
	v_mfma_f32_32x32x16_bf16 v[64:79], v[220:223], v[124:127], v[64:79]
	s_waitcnt lgkmcnt(1)
	v_mfma_f32_32x32x16_bf16 v[64:79], v[2:5], v[128:131], v[64:79]
	s_waitcnt lgkmcnt(0)
	v_mfma_f32_32x32x16_bf16 v[64:79], v[212:215], v[132:135], v[64:79]

.LBB0_252:
	v_sub_f32_e32 v3, v80, v1
	v_sub_f32_e32 v4, v81, v1
	v_sub_f32_e32 v5, v82, v1
	v_sub_f32_e32 v6, v83, v1
	v_sub_f32_e32 v7, v84, v1
	v_sub_f32_e32 v8, v85, v1
	v_sub_f32_e32 v9, v86, v1
	v_sub_f32_e32 v10, v87, v1
	v_exp_f32_e32 v3, v3
	v_exp_f32_e32 v4, v4
	v_exp_f32_e32 v5, v5
	v_exp_f32_e32 v6, v6
	v_exp_f32_e32 v7, v7
	v_exp_f32_e32 v8, v8
	v_exp_f32_e32 v9, v9
	v_exp_f32_e32 v10, v10
	v_sub_f32_e32 v86, v99, v1
	v_add_u32_e32 v99, v234, v230
	v_sub_f32_e32 v14, v91, v1
	v_sub_f32_e32 v15, v92, v1
	v_sub_f32_e32 v80, v93, v1
	v_sub_f32_e32 v81, v94, v1
	v_sub_f32_e32 v82, v95, v1
	v_sub_f32_e32 v83, v96, v1
	v_sub_f32_e32 v84, v97, v1
	v_sub_f32_e32 v85, v98, v1
	v_sub_f32_e32 v91, v104, v1
	v_sub_f32_e32 v92, v105, v1
	v_sub_f32_e32 v93, v106, v1
	v_sub_f32_e32 v94, v107, v1
	v_sub_f32_e32 v95, v108, v1
	v_sub_f32_e32 v96, v109, v1
	v_sub_f32_e32 v97, v110, v1
	v_sub_f32_e32 v98, v111, v1
	ds_read_b128 v[104:107], v99 offset:26624
	ds_read_b128 v[108:111], v99 offset:26656
	v_sub_f32_e32 v11, v88, v1
	v_sub_f32_e32 v12, v89, v1
	v_sub_f32_e32 v13, v90, v1
	v_sub_f32_e32 v87, v100, v1
	v_sub_f32_e32 v88, v101, v1
	v_sub_f32_e32 v89, v102, v1
	v_sub_f32_e32 v90, v103, v1
	v_cvt_pk_bf16_f32 v100, v3, v4
	v_cvt_pk_bf16_f32 v101, v5, v6
	v_cvt_pk_bf16_f32 v102, v7, v8
	v_cvt_pk_bf16_f32 v103, v9, v10
	v_exp_f32_e32 v11, v11
	v_exp_f32_e32 v12, v12
	s_waitcnt lgkmcnt(1)
	v_mfma_f32_32x32x16_bf16 v[32:47], v[104:107], v[100:103], v[32:47]
	ds_read_b128 v[104:107], v99 offset:35328
	v_exp_f32_e32 v13, v13
	v_exp_f32_e32 v14, v14
	v_exp_f32_e32 v15, v15
	v_exp_f32_e32 v80, v80
	v_exp_f32_e32 v81, v81
	v_exp_f32_e32 v82, v82
	s_waitcnt lgkmcnt(0)
	v_mfma_f32_32x32x16_bf16 v[16:31], v[104:107], v[100:103], v[16:31]
	ds_read_b128 v[104:107], v99 offset:35360
	v_cvt_pk_bf16_f32 v100, v11, v12
	v_cvt_pk_bf16_f32 v101, v13, v14
	v_cvt_pk_bf16_f32 v102, v15, v80
	v_cvt_pk_bf16_f32 v103, v81, v82
	v_exp_f32_e32 v83, v83
	v_exp_f32_e32 v84, v84
	v_mfma_f32_32x32x16_bf16 v[32:47], v[108:111], v[100:103], v[32:47]
	v_exp_f32_e32 v85, v85
	v_exp_f32_e32 v86, v86
	v_exp_f32_e32 v87, v87
	v_exp_f32_e32 v88, v88
	v_exp_f32_e32 v89, v89
	v_exp_f32_e32 v90, v90
	v_exp_f32_e32 v91, v91
	s_waitcnt lgkmcnt(0)
	v_mfma_f32_32x32x16_bf16 v[16:31], v[104:107], v[100:103], v[16:31]
	v_exp_f32_e32 v92, v92
	v_exp_f32_e32 v93, v93
	v_exp_f32_e32 v94, v94
	v_exp_f32_e32 v95, v95
	v_exp_f32_e32 v96, v96
	v_exp_f32_e32 v97, v97
	v_exp_f32_e32 v98, v98
	s_and_saveexec_b64 s[56:57], s[52:53]
	s_cbranch_execz .LBB0_254
	ds_read_b128 v[100:103], v99 offset:26688
	ds_read_b128 v[212:215], v99 offset:35392
	ds_read_b128 v[216:219], v99 offset:26720
	ds_read_b128 v[220:223], v99 offset:35424
	v_cvt_pk_bf16_f32 v104, v83, v84
	v_cvt_pk_bf16_f32 v105, v85, v86
	v_cvt_pk_bf16_f32 v106, v87, v88
	v_cvt_pk_bf16_f32 v107, v89, v90
	s_waitcnt lgkmcnt(3)
	s_nop 0
	v_mfma_f32_32x32x16_bf16 v[32:47], v[100:103], v[104:107], v[32:47]
	s_waitcnt lgkmcnt(2)
	v_mfma_f32_32x32x16_bf16 v[16:31], v[212:215], v[104:107], v[16:31]
	v_cvt_pk_bf16_f32 v104, v91, v92
	v_cvt_pk_bf16_f32 v105, v93, v94
	v_cvt_pk_bf16_f32 v106, v95, v96
	v_cvt_pk_bf16_f32 v107, v97, v98
	s_waitcnt lgkmcnt(1)
	s_nop 0
	v_mfma_f32_32x32x16_bf16 v[32:47], v[216:219], v[104:107], v[32:47]
	s_waitcnt lgkmcnt(0)
	v_mfma_f32_32x32x16_bf16 v[16:31], v[220:223], v[104:107], v[16:31]
.LBB0_254:
	s_or_b64 exec, exec, s[56:57]
	v_sub_f32_e32 v48, v48, v1
	v_sub_f32_e32 v49, v49, v1
	v_sub_f32_e32 v50, v50, v1
	v_sub_f32_e32 v51, v51, v1
	v_sub_f32_e32 v52, v52, v1
	v_sub_f32_e32 v53, v53, v1
	v_sub_f32_e32 v54, v54, v1
	v_sub_f32_e32 v55, v55, v1
	v_sub_f32_e32 v56, v56, v1
	v_sub_f32_e32 v57, v57, v1
	v_sub_f32_e32 v58, v58, v1
	v_sub_f32_e32 v59, v59, v1
	v_sub_f32_e32 v60, v60, v1
	v_sub_f32_e32 v61, v61, v1
	v_sub_f32_e32 v62, v62, v1
	v_sub_f32_e32 v63, v63, v1
	v_exp_f32_e32 v48, v48
	v_exp_f32_e32 v49, v49
	v_exp_f32_e32 v50, v50
	v_exp_f32_e32 v51, v51
	v_exp_f32_e32 v52, v52
	v_exp_f32_e32 v53, v53
	v_exp_f32_e32 v54, v54
	v_exp_f32_e32 v55, v55
	v_exp_f32_e32 v56, v56
	v_exp_f32_e32 v57, v57
	v_exp_f32_e32 v58, v58
	v_exp_f32_e32 v59, v59
	v_exp_f32_e32 v60, v60
	v_exp_f32_e32 v61, v61
	v_exp_f32_e32 v62, v62
	v_exp_f32_e32 v63, v63
	s_and_saveexec_b64 s[52:53], s[50:51]
	s_cbranch_execz .LBB0_256
	ds_read_b128 v[100:103], v99 offset:26752
	ds_read_b128 v[212:215], v99 offset:35456
	ds_read_b128 v[216:219], v99 offset:26784
	ds_read_b128 v[220:223], v99 offset:35488
	v_cvt_pk_bf16_f32 v104, v48, v49
	v_cvt_pk_bf16_f32 v105, v50, v51
	v_cvt_pk_bf16_f32 v106, v52, v53
	v_cvt_pk_bf16_f32 v107, v54, v55
	s_waitcnt lgkmcnt(3)
	s_nop 0
	v_mfma_f32_32x32x16_bf16 v[32:47], v[100:103], v[104:107], v[32:47]
	s_waitcnt lgkmcnt(2)
	v_mfma_f32_32x32x16_bf16 v[16:31], v[212:215], v[104:107], v[16:31]
	v_cvt_pk_bf16_f32 v104, v56, v57
	v_cvt_pk_bf16_f32 v105, v58, v59
	v_cvt_pk_bf16_f32 v106, v60, v61
	v_cvt_pk_bf16_f32 v107, v62, v63
	s_waitcnt lgkmcnt(1)
	s_nop 0
	v_mfma_f32_32x32x16_bf16 v[32:47], v[216:219], v[104:107], v[32:47]
	s_waitcnt lgkmcnt(0)
	v_mfma_f32_32x32x16_bf16 v[16:31], v[220:223], v[104:107], v[16:31]
.LBB0_256:
	s_or_b64 exec, exec, s[52:53]
	v_sub_f32_e32 v64, v64, v1
	v_sub_f32_e32 v65, v65, v1
	v_sub_f32_e32 v66, v66, v1
	v_sub_f32_e32 v67, v67, v1
	v_sub_f32_e32 v68, v68, v1
	v_sub_f32_e32 v69, v69, v1
	v_sub_f32_e32 v70, v70, v1
	v_sub_f32_e32 v71, v71, v1
	v_sub_f32_e32 v72, v72, v1
	v_sub_f32_e32 v73, v73, v1
	v_sub_f32_e32 v74, v74, v1
	v_sub_f32_e32 v75, v75, v1
	v_sub_f32_e32 v76, v76, v1
	v_sub_f32_e32 v77, v77, v1
	v_sub_f32_e32 v78, v78, v1
	v_sub_f32_e32 v79, v79, v1
	v_exp_f32_e32 v64, v64
	v_exp_f32_e32 v65, v65
	v_exp_f32_e32 v66, v66
	v_exp_f32_e32 v67, v67
	v_exp_f32_e32 v68, v68
	v_exp_f32_e32 v69, v69
	v_exp_f32_e32 v70, v70
	v_exp_f32_e32 v71, v71
	v_exp_f32_e32 v72, v72
	v_exp_f32_e32 v73, v73
	v_exp_f32_e32 v74, v74
	v_exp_f32_e32 v75, v75
	v_exp_f32_e32 v76, v76
	v_exp_f32_e32 v77, v77
	v_exp_f32_e32 v78, v78
	v_exp_f32_e32 v79, v79
	s_and_saveexec_b64 s[50:51], s[48:49]
	s_cbranch_execz .LBB0_258
	ds_read_b128 v[100:103], v99 offset:26816
	ds_read_b128 v[212:215], v99 offset:35520
	ds_read_b128 v[216:219], v99 offset:26848
	ds_read_b128 v[220:223], v99 offset:35552
	v_cvt_pk_bf16_f32 v104, v64, v65
	v_cvt_pk_bf16_f32 v105, v66, v67
	v_cvt_pk_bf16_f32 v106, v68, v69
	v_cvt_pk_bf16_f32 v107, v70, v71
	s_waitcnt lgkmcnt(3)
	s_nop 0
	v_mfma_f32_32x32x16_bf16 v[32:47], v[100:103], v[104:107], v[32:47]
	s_waitcnt lgkmcnt(2)
	v_mfma_f32_32x32x16_bf16 v[16:31], v[212:215], v[104:107], v[16:31]
	v_cvt_pk_bf16_f32 v104, v72, v73
	v_cvt_pk_bf16_f32 v105, v74, v75
	v_cvt_pk_bf16_f32 v106, v76, v77
	v_cvt_pk_bf16_f32 v107, v78, v79
	s_waitcnt lgkmcnt(1)
	s_nop 0
	v_mfma_f32_32x32x16_bf16 v[32:47], v[216:219], v[104:107], v[32:47]
	s_waitcnt lgkmcnt(0)
	v_mfma_f32_32x32x16_bf16 v[16:31], v[220:223], v[104:107], v[16:31]

.LBB0_259:
	s_or_b64 exec, exec, s[66:67]
	s_xor_b32 s2, s59, 1
	s_mul_i32 s2, s2, 0xac00
	v_lshl_add_u32 v1, v209, 1, s2
	s_cmp_lt_u32 s62, s78
	v_lshl_add_u32 v234, v206, 1, s2
	v_lshl_add_u32 v235, v208, 1, s2
	v_add_u32_e32 v236, 0x6800, v1
	v_add_u32_e32 v237, 0x8800, v1
	s_cselect_b64 s[56:57], -1, 0
	s_cmp_ge_u32 s62, s78
	s_waitcnt vmcnt(9)
	ds_write_b128 v234, v[136:139]
	s_waitcnt vmcnt(8)
	ds_write_b128 v234, v[140:143] offset:13312
	s_waitcnt vmcnt(7)
	ds_write_b128 v235, v[148:151] offset:128
	s_waitcnt vmcnt(6)
	ds_write2_b64 v236, v[152:153], v[154:155] offset1:2
	s_waitcnt vmcnt(5)
	ds_write2_b64 v237, v[160:161], v[162:163] offset0:64 offset1:66
	s_waitcnt lgkmcnt(0)
	s_barrier
	s_cbranch_scc1 .LBB0_279
	s_add_i32 s2, s81, -1
	v_readlane_b32 s48, v253, 7
	v_readlane_b32 s49, v253, 8
	s_min_i32 s48, s2, s78
	s_lshl_b64 s[2:3], s[48:49], 17
	v_lshl_add_u64 v[2:3], v[200:201], 0, s[2:3]
	v_add_co_u32_e32 v4, vcc, 0x10000, v2
	s_lshl_b64 s[2:3], s[48:49], 13
	s_nop 0
	v_addc_co_u32_e32 v5, vcc, 0, v3, vcc
	global_load_dwordx4 v[136:139], v[2:3], off
	global_load_dwordx4 v[140:143], v[4:5], off
	v_lshl_add_u64 v[2:3], v[202:203], 0, s[2:3]
	s_mov_b32 s3, s49
	v_writelane_b32 v253, s2, 7
	global_load_dwordx4 v[148:151], v[2:3], off
	s_nop 0
	v_writelane_b32 v253, s3, 8
	s_lshl_b64 s[2:3], s[48:49], 8
	v_lshl_add_u64 v[2:3], v[204:205], 0, s[2:3]
	v_add_co_u32_e32 v4, vcc, 0x82000, v2
	s_add_i32 s3, s81, -4
	s_nop 0
	v_addc_co_u32_e32 v5, vcc, 0, v3, vcc
	global_load_dwordx4 v[152:155], v[2:3], off
	global_load_dwordx4 v[160:163], v[4:5], off
	v_cmp_lt_i32_e32 vcc, s62, v199
	s_and_b32 s2, s3, 1
	s_and_b64 s[48:49], s[64:65], vcc
	s_and_saveexec_b64 s[66:67], s[48:49]
	s_cbranch_execz .LBB0_278
	s_mul_i32 s48, s2, 0xac00
	v_or_b32_e32 v239, s48, v196
	v_add_u32_e32 v240, v239, v229
	ds_read_b128 v[2:5], v240
	ds_read_b128 v[6:9], v240 offset:32
	v_cmp_ge_i32_e32 vcc, s3, v199
	v_mov_b32_e32 v62, v0
	v_mov_b32_e32 v63, v0
	s_waitcnt lgkmcnt(1)
	v_mfma_f32_32x32x16_bf16 v[80:95], v[2:5], v[112:115], 0
	v_cndmask_b32_e32 v1, 3, v228, vcc
	v_mov_b32_e32 v48, 0xf149f2ca
	v_mov_b32_e32 v49, v0
	v_mov_b32_e32 v50, v0
	v_mov_b32_e32 v51, v0
	v_mov_b32_e32 v52, v0
	v_mov_b32_e32 v53, v0
	s_waitcnt lgkmcnt(0)
	v_mfma_f32_32x32x16_bf16 v[80:95], v[6:9], v[116:119], v[80:95]
	ds_read_b128 v[2:5], v240 offset:64
	ds_read_b128 v[6:9], v240 offset:96
	v_mov_b32_e32 v54, v0
	v_mov_b32_e32 v55, v0
	v_mov_b32_e32 v56, v0
	v_mov_b32_e32 v57, v0
	v_mov_b32_e32 v58, v0
	v_mov_b32_e32 v59, v0
	s_waitcnt lgkmcnt(1)
	v_mfma_f32_32x32x16_bf16 v[80:95], v[2:5], v[120:123], v[80:95]
	ds_read_b128 v[2:5], v240 offset:128
	v_mov_b32_e32 v60, v0
	v_mov_b32_e32 v61, v0
	v_mov_b64_e32 v[110:111], v[62:63]
	v_cmp_ne_u32_e64 s[52:53], 0, v1
	v_mov_b64_e32 v[108:109], v[60:61]
	v_mov_b64_e32 v[106:107], v[58:59]
	s_waitcnt lgkmcnt(1)
	v_mfma_f32_32x32x16_bf16 v[80:95], v[6:9], v[124:127], v[80:95]
	ds_read_b128 v[6:9], v240 offset:160
	v_mov_b64_e32 v[104:105], v[56:57]
	v_mov_b64_e32 v[102:103], v[54:55]
	v_mov_b64_e32 v[100:101], v[52:53]
	v_mov_b64_e32 v[98:99], v[50:51]
	v_mov_b64_e32 v[96:97], v[48:49]
	s_waitcnt lgkmcnt(1)
	v_mfma_f32_32x32x16_bf16 v[80:95], v[2:5], v[128:131], v[80:95]
	s_waitcnt lgkmcnt(0)
	v_mfma_f32_32x32x16_bf16 v[80:95], v[6:9], v[132:135], v[80:95]
	s_and_saveexec_b64 s[48:49], s[52:53]
	s_cbranch_execz .LBB0_263
	ds_read_b128 v[2:5], v240 offset:6656
	ds_read_b128 v[212:215], v240 offset:6688
	ds_read_b128 v[216:219], v240 offset:6720
	ds_read_b128 v[220:223], v240 offset:6752
	s_waitcnt lgkmcnt(3)
	v_mfma_f32_32x32x16_bf16 v[96:111], v[2:5], v[112:115], 0
	ds_read_b128 v[2:5], v240 offset:6784
	s_waitcnt lgkmcnt(3)
	v_mfma_f32_32x32x16_bf16 v[96:111], v[212:215], v[116:119], v[96:111]
	ds_read_b128 v[212:215], v240 offset:6816
	s_waitcnt lgkmcnt(3)
	v_mfma_f32_32x32x16_bf16 v[96:111], v[216:219], v[120:123], v[96:111]
	s_waitcnt lgkmcnt(2)
	v_mfma_f32_32x32x16_bf16 v[96:111], v[220:223], v[124:127], v[96:111]
	s_waitcnt lgkmcnt(1)
	v_mfma_f32_32x32x16_bf16 v[96:111], v[2:5], v[128:131], v[96:111]
	s_waitcnt lgkmcnt(0)
	v_mfma_f32_32x32x16_bf16 v[96:111], v[212:215], v[132:135], v[96:111]
.LBB0_263:
	s_or_b64 exec, exec, s[48:49]
	v_cmp_lt_u32_e64 s[50:51], 1, v1
	s_and_saveexec_b64 s[48:49], s[50:51]
	s_cbranch_execz .LBB0_265
	ds_read_b128 v[2:5], v240 offset:13312
	ds_read_b128 v[212:215], v240 offset:13344
	ds_read_b128 v[216:219], v240 offset:13376
	ds_read_b128 v[220:223], v240 offset:13408
	s_waitcnt lgkmcnt(3)
	v_mfma_f32_32x32x16_bf16 v[48:63], v[2:5], v[112:115], 0
	ds_read_b128 v[2:5], v240 offset:13440
	s_waitcnt lgkmcnt(3)
	v_mfma_f32_32x32x16_bf16 v[48:63], v[212:215], v[116:119], v[48:63]
	ds_read_b128 v[212:215], v240 offset:13472
	s_waitcnt lgkmcnt(3)
	v_mfma_f32_32x32x16_bf16 v[48:63], v[216:219], v[120:123], v[48:63]
	s_waitcnt lgkmcnt(2)
	v_mfma_f32_32x32x16_bf16 v[48:63], v[220:223], v[124:127], v[48:63]
	s_waitcnt lgkmcnt(1)
	v_mfma_f32_32x32x16_bf16 v[48:63], v[2:5], v[128:131], v[48:63]
	s_waitcnt lgkmcnt(0)
	v_mfma_f32_32x32x16_bf16 v[48:63], v[212:215], v[132:135], v[48:63]
.LBB0_265:
	s_or_b64 exec, exec, s[48:49]
	v_mov_b32_e32 v14, v0
	v_mov_b32_e32 v15, v0
	v_cmp_eq_u32_e64 s[48:49], 3, v1
	v_mov_b32_e32 v1, v0
	v_mov_b32_e32 v2, v0
	v_mov_b32_e32 v3, v0
	v_mov_b32_e32 v4, v0
	v_mov_b32_e32 v5, v0
	v_mov_b32_e32 v6, v0
	v_mov_b32_e32 v7, v0
	v_mov_b32_e32 v8, v0
	v_mov_b32_e32 v9, v0
	v_mov_b32_e32 v10, v0
	v_mov_b32_e32 v11, v0
	v_mov_b32_e32 v12, v0
	v_mov_b32_e32 v13, v0
	v_mov_b64_e32 v[78:79], v[14:15]
	v_mov_b64_e32 v[76:77], v[12:13]
	v_mov_b64_e32 v[74:75], v[10:11]
	v_mov_b64_e32 v[72:73], v[8:9]
	v_mov_b64_e32 v[70:71], v[6:7]
	v_mov_b64_e32 v[68:69], v[4:5]
	v_mov_b64_e32 v[66:67], v[2:3]
	v_mov_b64_e32 v[64:65], v[0:1]
	s_and_saveexec_b64 s[62:63], s[48:49]
	s_cbranch_execz .LBB0_267
	ds_read_b128 v[2:5], v240 offset:19968
	ds_read_b128 v[212:215], v240 offset:20000
	ds_read_b128 v[216:219], v240 offset:20032
	ds_read_b128 v[220:223], v240 offset:20064
	s_waitcnt lgkmcnt(3)
	v_mfma_f32_32x32x16_bf16 v[64:79], v[2:5], v[112:115], 0
	ds_read_b128 v[2:5], v240 offset:20096
	s_waitcnt lgkmcnt(3)
	v_mfma_f32_32x32x16_bf16 v[64:79], v[212:215], v[116:119], v[64:79]
	ds_read_b128 v[212:215], v240 offset:20128
	s_waitcnt lgkmcnt(3)
	v_mfma_f32_32x32x16_bf16 v[64:79], v[216:219], v[120:123], v[64:79]
	s_waitcnt lgkmcnt(2)
	v_mfma_f32_32x32x16_bf16 v[64:79], v[220:223], v[124:127], v[64:79]
	s_waitcnt lgkmcnt(1)
	v_mfma_f32_32x32x16_bf16 v[64:79], v[2:5], v[128:131], v[64:79]
	s_waitcnt lgkmcnt(0)
	v_mfma_f32_32x32x16_bf16 v[64:79], v[212:215], v[132:135], v[64:79]

.LBB0_271:
	v_sub_f32_e32 v3, v80, v1
	v_sub_f32_e32 v4, v81, v1
	v_sub_f32_e32 v5, v82, v1
	v_sub_f32_e32 v6, v83, v1
	v_sub_f32_e32 v7, v84, v1
	v_sub_f32_e32 v8, v85, v1
	v_sub_f32_e32 v9, v86, v1
	v_sub_f32_e32 v10, v87, v1
	v_exp_f32_e32 v3, v3
	v_exp_f32_e32 v4, v4
	v_exp_f32_e32 v5, v5
	v_exp_f32_e32 v6, v6
	v_exp_f32_e32 v7, v7
	v_exp_f32_e32 v8, v8
	v_exp_f32_e32 v9, v9
	v_exp_f32_e32 v10, v10
	v_sub_f32_e32 v86, v99, v1
	v_add_u32_e32 v99, v239, v230
	v_sub_f32_e32 v14, v91, v1
	v_sub_f32_e32 v15, v92, v1
	v_sub_f32_e32 v80, v93, v1
	v_sub_f32_e32 v81, v94, v1
	v_sub_f32_e32 v82, v95, v1
	v_sub_f32_e32 v83, v96, v1
	v_sub_f32_e32 v84, v97, v1
	v_sub_f32_e32 v85, v98, v1
	v_sub_f32_e32 v91, v104, v1
	v_sub_f32_e32 v92, v105, v1
	v_sub_f32_e32 v93, v106, v1
	v_sub_f32_e32 v94, v107, v1
	v_sub_f32_e32 v95, v108, v1
	v_sub_f32_e32 v96, v109, v1
	v_sub_f32_e32 v97, v110, v1
	v_sub_f32_e32 v98, v111, v1
	ds_read_b128 v[104:107], v99 offset:26624
	ds_read_b128 v[108:111], v99 offset:26656
	v_sub_f32_e32 v11, v88, v1
	v_sub_f32_e32 v12, v89, v1
	v_sub_f32_e32 v13, v90, v1
	v_sub_f32_e32 v87, v100, v1
	v_sub_f32_e32 v88, v101, v1
	v_sub_f32_e32 v89, v102, v1
	v_sub_f32_e32 v90, v103, v1
	v_cvt_pk_bf16_f32 v100, v3, v4
	v_cvt_pk_bf16_f32 v101, v5, v6
	v_cvt_pk_bf16_f32 v102, v7, v8
	v_cvt_pk_bf16_f32 v103, v9, v10
	v_exp_f32_e32 v11, v11
	v_exp_f32_e32 v12, v12
	s_waitcnt lgkmcnt(1)
	v_mfma_f32_32x32x16_bf16 v[32:47], v[104:107], v[100:103], v[32:47]
	ds_read_b128 v[104:107], v99 offset:35328
	v_exp_f32_e32 v13, v13
	v_exp_f32_e32 v14, v14
	v_exp_f32_e32 v15, v15
	v_exp_f32_e32 v80, v80
	v_exp_f32_e32 v81, v81
	v_exp_f32_e32 v82, v82
	s_waitcnt lgkmcnt(0)
	v_mfma_f32_32x32x16_bf16 v[16:31], v[104:107], v[100:103], v[16:31]
	ds_read_b128 v[104:107], v99 offset:35360
	v_cvt_pk_bf16_f32 v100, v11, v12
	v_cvt_pk_bf16_f32 v101, v13, v14
	v_cvt_pk_bf16_f32 v102, v15, v80
	v_cvt_pk_bf16_f32 v103, v81, v82
	v_exp_f32_e32 v83, v83
	v_exp_f32_e32 v84, v84
	v_mfma_f32_32x32x16_bf16 v[32:47], v[108:111], v[100:103], v[32:47]
	v_exp_f32_e32 v85, v85
	v_exp_f32_e32 v86, v86
	v_exp_f32_e32 v87, v87
	v_exp_f32_e32 v88, v88
	v_exp_f32_e32 v89, v89
	v_exp_f32_e32 v90, v90
	v_exp_f32_e32 v91, v91
	s_waitcnt lgkmcnt(0)
	v_mfma_f32_32x32x16_bf16 v[16:31], v[104:107], v[100:103], v[16:31]
	v_exp_f32_e32 v92, v92
	v_exp_f32_e32 v93, v93
	v_exp_f32_e32 v94, v94
	v_exp_f32_e32 v95, v95
	v_exp_f32_e32 v96, v96
	v_exp_f32_e32 v97, v97
	v_exp_f32_e32 v98, v98
	s_and_saveexec_b64 s[70:71], s[52:53]
	s_cbranch_execz .LBB0_273
	ds_read_b128 v[100:103], v99 offset:26688
	ds_read_b128 v[212:215], v99 offset:35392
	ds_read_b128 v[216:219], v99 offset:26720
	ds_read_b128 v[220:223], v99 offset:35424
	v_cvt_pk_bf16_f32 v104, v83, v84
	v_cvt_pk_bf16_f32 v105, v85, v86
	v_cvt_pk_bf16_f32 v106, v87, v88
	v_cvt_pk_bf16_f32 v107, v89, v90
	s_waitcnt lgkmcnt(3)
	s_nop 0
	v_mfma_f32_32x32x16_bf16 v[32:47], v[100:103], v[104:107], v[32:47]
	s_waitcnt lgkmcnt(2)
	v_mfma_f32_32x32x16_bf16 v[16:31], v[212:215], v[104:107], v[16:31]
	v_cvt_pk_bf16_f32 v104, v91, v92
	v_cvt_pk_bf16_f32 v105, v93, v94
	v_cvt_pk_bf16_f32 v106, v95, v96
	v_cvt_pk_bf16_f32 v107, v97, v98
	s_waitcnt lgkmcnt(1)
	s_nop 0
	v_mfma_f32_32x32x16_bf16 v[32:47], v[216:219], v[104:107], v[32:47]
	s_waitcnt lgkmcnt(0)
	v_mfma_f32_32x32x16_bf16 v[16:31], v[220:223], v[104:107], v[16:31]
.LBB0_273:
	s_or_b64 exec, exec, s[70:71]
	v_sub_f32_e32 v48, v48, v1
	v_sub_f32_e32 v49, v49, v1
	v_sub_f32_e32 v50, v50, v1
	v_sub_f32_e32 v51, v51, v1
	v_sub_f32_e32 v52, v52, v1
	v_sub_f32_e32 v53, v53, v1
	v_sub_f32_e32 v54, v54, v1
	v_sub_f32_e32 v55, v55, v1
	v_sub_f32_e32 v56, v56, v1
	v_sub_f32_e32 v57, v57, v1
	v_sub_f32_e32 v58, v58, v1
	v_sub_f32_e32 v59, v59, v1
	v_sub_f32_e32 v60, v60, v1
	v_sub_f32_e32 v61, v61, v1
	v_sub_f32_e32 v62, v62, v1
	v_sub_f32_e32 v63, v63, v1
	v_exp_f32_e32 v48, v48
	v_exp_f32_e32 v49, v49
	v_exp_f32_e32 v50, v50
	v_exp_f32_e32 v51, v51
	v_exp_f32_e32 v52, v52
	v_exp_f32_e32 v53, v53
	v_exp_f32_e32 v54, v54
	v_exp_f32_e32 v55, v55
	v_exp_f32_e32 v56, v56
	v_exp_f32_e32 v57, v57
	v_exp_f32_e32 v58, v58
	v_exp_f32_e32 v59, v59
	v_exp_f32_e32 v60, v60
	v_exp_f32_e32 v61, v61
	v_exp_f32_e32 v62, v62
	v_exp_f32_e32 v63, v63
	s_and_saveexec_b64 s[52:53], s[50:51]
	s_cbranch_execz .LBB0_275
	ds_read_b128 v[100:103], v99 offset:26752
	ds_read_b128 v[212:215], v99 offset:35456
	ds_read_b128 v[216:219], v99 offset:26784
	ds_read_b128 v[220:223], v99 offset:35488
	v_cvt_pk_bf16_f32 v104, v48, v49
	v_cvt_pk_bf16_f32 v105, v50, v51
	v_cvt_pk_bf16_f32 v106, v52, v53
	v_cvt_pk_bf16_f32 v107, v54, v55
	s_waitcnt lgkmcnt(3)
	s_nop 0
	v_mfma_f32_32x32x16_bf16 v[32:47], v[100:103], v[104:107], v[32:47]
	s_waitcnt lgkmcnt(2)
	v_mfma_f32_32x32x16_bf16 v[16:31], v[212:215], v[104:107], v[16:31]
	v_cvt_pk_bf16_f32 v104, v56, v57
	v_cvt_pk_bf16_f32 v105, v58, v59
	v_cvt_pk_bf16_f32 v106, v60, v61
	v_cvt_pk_bf16_f32 v107, v62, v63
	s_waitcnt lgkmcnt(1)
	s_nop 0
	v_mfma_f32_32x32x16_bf16 v[32:47], v[216:219], v[104:107], v[32:47]
	s_waitcnt lgkmcnt(0)
	v_mfma_f32_32x32x16_bf16 v[16:31], v[220:223], v[104:107], v[16:31]

.LBB0_279:
	s_andn2_b64 vcc, exec, s[56:57]
	s_cbranch_vccnz .LBB0_240
	s_add_i32 s2, s81, -3
	s_cmp_gt_u32 s2, s78
	s_cbranch_scc1 .LBB0_240
	v_readlane_b32 s48, v253, 7
	v_readlane_b32 s49, v253, 8
	s_mov_b32 s51, s49
	s_min_i32 s50, s81, s78
	s_lshl_b64 s[48:49], s[50:51], 17
	v_lshl_add_u64 v[2:3], v[200:201], 0, s[48:49]
	v_add_co_u32_e32 v4, vcc, 0x10000, v2
	s_lshl_b64 s[48:49], s[50:51], 13
	s_nop 0
	v_addc_co_u32_e32 v5, vcc, 0, v3, vcc
	global_load_dwordx4 v[144:147], v[2:3], off
	global_load_dwordx4 v[156:159], v[4:5], off
	v_lshl_add_u64 v[2:3], v[202:203], 0, s[48:49]
	s_lshl_b64 s[48:49], s[50:51], 8
	global_load_dwordx4 v[164:167], v[2:3], off
	v_lshl_add_u64 v[2:3], v[204:205], 0, s[48:49]
	v_add_co_u32_e32 v4, vcc, 0x82000, v2
	s_mov_b32 s3, s51
	s_nop 0
	v_addc_co_u32_e32 v5, vcc, 0, v3, vcc
	global_load_dwordx4 v[168:171], v[2:3], off
	global_load_dwordx4 v[172:175], v[4:5], off
	v_writelane_b32 v253, s2, 7
	s_nop 1
	v_cmp_le_i32_e32 vcc, s2, v199
	v_writelane_b32 v253, s3, 8
	s_and_b64 s[48:49], s[64:65], vcc
	s_and_saveexec_b64 s[56:57], s[48:49]
	s_cbranch_execz .LBB0_239
	s_mul_i32 s59, s59, 0xac00
	v_or_b32_e32 v239, s59, v196
	v_add_u32_e32 v240, v239, v229
	ds_read_b128 v[2:5], v240
	ds_read_b128 v[6:9], v240 offset:32
	v_cmp_ge_i32_e32 vcc, s2, v199
	v_mov_b32_e32 v62, v0
	v_mov_b32_e32 v63, v0
	s_waitcnt lgkmcnt(1)
	v_mfma_f32_32x32x16_bf16 v[80:95], v[2:5], v[112:115], 0
	v_cndmask_b32_e32 v1, 3, v228, vcc
	v_mov_b32_e32 v48, 0xf149f2ca
	v_mov_b32_e32 v49, v0
	v_mov_b32_e32 v50, v0
	v_mov_b32_e32 v51, v0
	v_mov_b32_e32 v52, v0
	v_mov_b32_e32 v53, v0
	s_waitcnt lgkmcnt(0)
	v_mfma_f32_32x32x16_bf16 v[80:95], v[6:9], v[116:119], v[80:95]
	ds_read_b128 v[2:5], v240 offset:64
	ds_read_b128 v[6:9], v240 offset:96
	v_mov_b32_e32 v54, v0
	v_mov_b32_e32 v55, v0
	v_mov_b32_e32 v56, v0
	v_mov_b32_e32 v57, v0
	v_mov_b32_e32 v58, v0
	v_mov_b32_e32 v59, v0
	s_waitcnt lgkmcnt(1)
	v_mfma_f32_32x32x16_bf16 v[80:95], v[2:5], v[120:123], v[80:95]
	ds_read_b128 v[2:5], v240 offset:128
	v_mov_b32_e32 v60, v0
	v_mov_b32_e32 v61, v0
	v_mov_b64_e32 v[110:111], v[62:63]
	v_cmp_ne_u32_e64 s[52:53], 0, v1
	v_mov_b64_e32 v[108:109], v[60:61]
	v_mov_b64_e32 v[106:107], v[58:59]
	s_waitcnt lgkmcnt(1)
	v_mfma_f32_32x32x16_bf16 v[80:95], v[6:9], v[124:127], v[80:95]
	ds_read_b128 v[6:9], v240 offset:160
	v_mov_b64_e32 v[104:105], v[56:57]
	v_mov_b64_e32 v[102:103], v[54:55]
	v_mov_b64_e32 v[100:101], v[52:53]
	v_mov_b64_e32 v[98:99], v[50:51]
	v_mov_b64_e32 v[96:97], v[48:49]
	s_waitcnt lgkmcnt(1)
	v_mfma_f32_32x32x16_bf16 v[80:95], v[2:5], v[128:131], v[80:95]
	s_waitcnt lgkmcnt(0)
	v_mfma_f32_32x32x16_bf16 v[80:95], v[6:9], v[132:135], v[80:95]
	s_and_saveexec_b64 s[48:49], s[52:53]
	s_cbranch_execz .LBB0_284
	ds_read_b128 v[2:5], v240 offset:6656
	ds_read_b128 v[212:215], v240 offset:6688
	ds_read_b128 v[216:219], v240 offset:6720
	ds_read_b128 v[220:223], v240 offset:6752
	s_waitcnt lgkmcnt(3)
	v_mfma_f32_32x32x16_bf16 v[96:111], v[2:5], v[112:115], 0
	ds_read_b128 v[2:5], v240 offset:6784
	s_waitcnt lgkmcnt(3)
	v_mfma_f32_32x32x16_bf16 v[96:111], v[212:215], v[116:119], v[96:111]
	ds_read_b128 v[212:215], v240 offset:6816
	s_waitcnt lgkmcnt(3)
	v_mfma_f32_32x32x16_bf16 v[96:111], v[216:219], v[120:123], v[96:111]
	s_waitcnt lgkmcnt(2)
	v_mfma_f32_32x32x16_bf16 v[96:111], v[220:223], v[124:127], v[96:111]
	s_waitcnt lgkmcnt(1)
	v_mfma_f32_32x32x16_bf16 v[96:111], v[2:5], v[128:131], v[96:111]
	s_waitcnt lgkmcnt(0)
	v_mfma_f32_32x32x16_bf16 v[96:111], v[212:215], v[132:135], v[96:111]

.LBB0_292:
	v_sub_f32_e32 v3, v80, v1
	v_sub_f32_e32 v4, v81, v1
	v_sub_f32_e32 v5, v82, v1
	v_sub_f32_e32 v6, v83, v1
	v_sub_f32_e32 v7, v84, v1
	v_sub_f32_e32 v8, v85, v1
	v_sub_f32_e32 v9, v86, v1
	v_sub_f32_e32 v10, v87, v1
	v_exp_f32_e32 v3, v3
	v_exp_f32_e32 v4, v4
	v_exp_f32_e32 v5, v5
	v_exp_f32_e32 v6, v6
	v_exp_f32_e32 v7, v7
	v_exp_f32_e32 v8, v8
	v_exp_f32_e32 v9, v9
	v_exp_f32_e32 v10, v10
	v_sub_f32_e32 v86, v99, v1
	v_add_u32_e32 v99, v239, v230
	v_sub_f32_e32 v14, v91, v1
	v_sub_f32_e32 v15, v92, v1
	v_sub_f32_e32 v80, v93, v1
	v_sub_f32_e32 v81, v94, v1
	v_sub_f32_e32 v82, v95, v1
	v_sub_f32_e32 v83, v96, v1
	v_sub_f32_e32 v84, v97, v1
	v_sub_f32_e32 v85, v98, v1
	v_sub_f32_e32 v91, v104, v1
	v_sub_f32_e32 v92, v105, v1
	v_sub_f32_e32 v93, v106, v1
	v_sub_f32_e32 v94, v107, v1
	v_sub_f32_e32 v95, v108, v1
	v_sub_f32_e32 v96, v109, v1
	v_sub_f32_e32 v97, v110, v1
	v_sub_f32_e32 v98, v111, v1
	ds_read_b128 v[104:107], v99 offset:26624
	ds_read_b128 v[108:111], v99 offset:26656
	v_sub_f32_e32 v11, v88, v1
	v_sub_f32_e32 v12, v89, v1
	v_sub_f32_e32 v13, v90, v1
	v_sub_f32_e32 v87, v100, v1
	v_sub_f32_e32 v88, v101, v1
	v_sub_f32_e32 v89, v102, v1
	v_sub_f32_e32 v90, v103, v1
	v_cvt_pk_bf16_f32 v100, v3, v4
	v_cvt_pk_bf16_f32 v101, v5, v6
	v_cvt_pk_bf16_f32 v102, v7, v8
	v_cvt_pk_bf16_f32 v103, v9, v10
	v_exp_f32_e32 v11, v11
	v_exp_f32_e32 v12, v12
	s_waitcnt lgkmcnt(1)
	v_mfma_f32_32x32x16_bf16 v[32:47], v[104:107], v[100:103], v[32:47]
	ds_read_b128 v[104:107], v99 offset:35328
	v_exp_f32_e32 v13, v13
	v_exp_f32_e32 v14, v14
	v_exp_f32_e32 v15, v15
	v_exp_f32_e32 v80, v80
	v_exp_f32_e32 v81, v81
	v_exp_f32_e32 v82, v82
	s_waitcnt lgkmcnt(0)
	v_mfma_f32_32x32x16_bf16 v[16:31], v[104:107], v[100:103], v[16:31]
	ds_read_b128 v[104:107], v99 offset:35360
	v_cvt_pk_bf16_f32 v100, v11, v12
	v_cvt_pk_bf16_f32 v101, v13, v14
	v_cvt_pk_bf16_f32 v102, v15, v80
	v_cvt_pk_bf16_f32 v103, v81, v82
	v_exp_f32_e32 v83, v83
	v_exp_f32_e32 v84, v84
	v_mfma_f32_32x32x16_bf16 v[32:47], v[108:111], v[100:103], v[32:47]
	v_exp_f32_e32 v85, v85
	v_exp_f32_e32 v86, v86
	v_exp_f32_e32 v87, v87
	v_exp_f32_e32 v88, v88
	v_exp_f32_e32 v89, v89
	v_exp_f32_e32 v90, v90
	v_exp_f32_e32 v91, v91
	s_waitcnt lgkmcnt(0)
	v_mfma_f32_32x32x16_bf16 v[16:31], v[104:107], v[100:103], v[16:31]
	v_exp_f32_e32 v92, v92
	v_exp_f32_e32 v93, v93
	v_exp_f32_e32 v94, v94
	v_exp_f32_e32 v95, v95
	v_exp_f32_e32 v96, v96
	v_exp_f32_e32 v97, v97
	v_exp_f32_e32 v98, v98
	s_and_saveexec_b64 s[64:65], s[52:53]
	s_cbranch_execz .LBB0_294
	ds_read_b128 v[100:103], v99 offset:26688
	ds_read_b128 v[212:215], v99 offset:35392
	ds_read_b128 v[216:219], v99 offset:26720
	ds_read_b128 v[220:223], v99 offset:35424
	v_cvt_pk_bf16_f32 v104, v83, v84
	v_cvt_pk_bf16_f32 v105, v85, v86
	v_cvt_pk_bf16_f32 v106, v87, v88
	v_cvt_pk_bf16_f32 v107, v89, v90
	s_waitcnt lgkmcnt(3)
	s_nop 0
	v_mfma_f32_32x32x16_bf16 v[32:47], v[100:103], v[104:107], v[32:47]
	s_waitcnt lgkmcnt(2)
	v_mfma_f32_32x32x16_bf16 v[16:31], v[212:215], v[104:107], v[16:31]
	v_cvt_pk_bf16_f32 v104, v91, v92
	v_cvt_pk_bf16_f32 v105, v93, v94
	v_cvt_pk_bf16_f32 v106, v95, v96
	v_cvt_pk_bf16_f32 v107, v97, v98
	s_waitcnt lgkmcnt(1)
	s_nop 0
	v_mfma_f32_32x32x16_bf16 v[32:47], v[216:219], v[104:107], v[32:47]
	s_waitcnt lgkmcnt(0)
	v_mfma_f32_32x32x16_bf16 v[16:31], v[220:223], v[104:107], v[16:31]
.LBB0_294:
	s_or_b64 exec, exec, s[64:65]
	v_sub_f32_e32 v48, v48, v1
	v_sub_f32_e32 v49, v49, v1
	v_sub_f32_e32 v50, v50, v1
	v_sub_f32_e32 v51, v51, v1
	v_sub_f32_e32 v52, v52, v1
	v_sub_f32_e32 v53, v53, v1
	v_sub_f32_e32 v54, v54, v1
	v_sub_f32_e32 v55, v55, v1
	v_sub_f32_e32 v56, v56, v1
	v_sub_f32_e32 v57, v57, v1
	v_sub_f32_e32 v58, v58, v1
	v_sub_f32_e32 v59, v59, v1
	v_sub_f32_e32 v60, v60, v1
	v_sub_f32_e32 v61, v61, v1
	v_sub_f32_e32 v62, v62, v1
	v_sub_f32_e32 v63, v63, v1
	v_exp_f32_e32 v48, v48
	v_exp_f32_e32 v49, v49
	v_exp_f32_e32 v50, v50
	v_exp_f32_e32 v51, v51
	v_exp_f32_e32 v52, v52
	v_exp_f32_e32 v53, v53
	v_exp_f32_e32 v54, v54
	v_exp_f32_e32 v55, v55
	v_exp_f32_e32 v56, v56
	v_exp_f32_e32 v57, v57
	v_exp_f32_e32 v58, v58
	v_exp_f32_e32 v59, v59
	v_exp_f32_e32 v60, v60
	v_exp_f32_e32 v61, v61
	v_exp_f32_e32 v62, v62
	v_exp_f32_e32 v63, v63
	s_and_saveexec_b64 s[52:53], s[50:51]
	s_cbranch_execz .LBB0_296
	ds_read_b128 v[100:103], v99 offset:26752
	ds_read_b128 v[212:215], v99 offset:35456
	ds_read_b128 v[216:219], v99 offset:26784
	ds_read_b128 v[220:223], v99 offset:35488
	v_cvt_pk_bf16_f32 v104, v48, v49
	v_cvt_pk_bf16_f32 v105, v50, v51
	v_cvt_pk_bf16_f32 v106, v52, v53
	v_cvt_pk_bf16_f32 v107, v54, v55
	s_waitcnt lgkmcnt(3)
	s_nop 0
	v_mfma_f32_32x32x16_bf16 v[32:47], v[100:103], v[104:107], v[32:47]
	s_waitcnt lgkmcnt(2)
	v_mfma_f32_32x32x16_bf16 v[16:31], v[212:215], v[104:107], v[16:31]
	v_cvt_pk_bf16_f32 v104, v56, v57
	v_cvt_pk_bf16_f32 v105, v58, v59
	v_cvt_pk_bf16_f32 v106, v60, v61
	v_cvt_pk_bf16_f32 v107, v62, v63
	s_waitcnt lgkmcnt(1)
	s_nop 0
	v_mfma_f32_32x32x16_bf16 v[32:47], v[216:219], v[104:107], v[32:47]
	s_waitcnt lgkmcnt(0)
	v_mfma_f32_32x32x16_bf16 v[16:31], v[220:223], v[104:107], v[16:31]
.LBB0_296:
	s_or_b64 exec, exec, s[52:53]
	v_sub_f32_e32 v64, v64, v1
	v_sub_f32_e32 v65, v65, v1
	v_sub_f32_e32 v66, v66, v1
	v_sub_f32_e32 v67, v67, v1
	v_sub_f32_e32 v68, v68, v1
	v_sub_f32_e32 v69, v69, v1
	v_sub_f32_e32 v70, v70, v1
	v_sub_f32_e32 v71, v71, v1
	v_sub_f32_e32 v72, v72, v1
	v_sub_f32_e32 v73, v73, v1
	v_sub_f32_e32 v74, v74, v1
	v_sub_f32_e32 v75, v75, v1
	v_sub_f32_e32 v76, v76, v1
	v_sub_f32_e32 v77, v77, v1
	v_sub_f32_e32 v78, v78, v1
	v_sub_f32_e32 v79, v79, v1
	v_exp_f32_e32 v64, v64
	v_exp_f32_e32 v65, v65
	v_exp_f32_e32 v66, v66
	v_exp_f32_e32 v67, v67
	v_exp_f32_e32 v68, v68
	v_exp_f32_e32 v69, v69
	v_exp_f32_e32 v70, v70
	v_exp_f32_e32 v71, v71
	v_exp_f32_e32 v72, v72
	v_exp_f32_e32 v73, v73
	v_exp_f32_e32 v74, v74
	v_exp_f32_e32 v75, v75
	v_exp_f32_e32 v76, v76
	v_exp_f32_e32 v77, v77
	v_exp_f32_e32 v78, v78
	v_exp_f32_e32 v79, v79
	s_and_saveexec_b64 s[50:51], s[48:49]
	s_cbranch_execz .LBB0_238
	ds_read_b128 v[100:103], v99 offset:26816
	ds_read_b128 v[212:215], v99 offset:35520
	ds_read_b128 v[216:219], v99 offset:26848
	ds_read_b128 v[220:223], v99 offset:35552
	v_cvt_pk_bf16_f32 v104, v64, v65
	v_cvt_pk_bf16_f32 v105, v66, v67
	v_cvt_pk_bf16_f32 v106, v68, v69
	v_cvt_pk_bf16_f32 v107, v70, v71
	s_waitcnt lgkmcnt(3)
	s_nop 0
	v_mfma_f32_32x32x16_bf16 v[32:47], v[100:103], v[104:107], v[32:47]
	s_waitcnt lgkmcnt(2)
	v_mfma_f32_32x32x16_bf16 v[16:31], v[212:215], v[104:107], v[16:31]
	v_cvt_pk_bf16_f32 v104, v72, v73
	v_cvt_pk_bf16_f32 v105, v74, v75
	v_cvt_pk_bf16_f32 v106, v76, v77
	v_cvt_pk_bf16_f32 v107, v78, v79
	s_waitcnt lgkmcnt(1)
	s_nop 0
	v_mfma_f32_32x32x16_bf16 v[32:47], v[216:219], v[104:107], v[32:47]
	s_waitcnt lgkmcnt(0)
	v_mfma_f32_32x32x16_bf16 v[16:31], v[220:223], v[104:107], v[16:31]
	s_branch .LBB0_238

.LBB0_569:
	s_or_b64 exec, exec, s[16:17]
	v_lshl_add_u64 v[82:83], v[120:121], 0, s[70:71]
	v_add_co_u32_e32 v212, vcc, 0x1000, v82
	s_nop 1
	v_addc_co_u32_e32 v213, vcc, 0, v83, vcc
	global_load_ushort v189, v[212:213], off
	v_add_co_u32_e32 v214, vcc, 0x7000, v82
	s_nop 1
	v_addc_co_u32_e32 v215, vcc, 0, v83, vcc
	global_load_ushort v190, v[214:215], off offset:960
	v_add_co_u32_e32 v212, vcc, 0x9000, v82
	s_nop 1
	v_addc_co_u32_e32 v213, vcc, 0, v83, vcc
	global_load_ushort v191, v[212:213], off offset:1280
	v_add_co_u32_e32 v214, vcc, s22, v82
	s_nop 1
	v_addc_co_u32_e32 v215, vcc, 0, v83, vcc
	global_load_ushort v192, v[214:215], off offset:1600
	v_add_co_u32_e32 v212, vcc, 0xd000, v82
	s_nop 1
	v_addc_co_u32_e32 v213, vcc, 0, v83, vcc
	global_load_ushort v193, v[212:213], off offset:1920
	v_add_co_u32_e32 v214, vcc, 0xf000, v82
	s_nop 1
	v_addc_co_u32_e32 v215, vcc, 0, v83, vcc
	global_load_ushort v194, v[214:215], off offset:2240
	v_add_co_u32_e32 v212, vcc, 0x3000, v82
	s_nop 1
	v_addc_co_u32_e32 v213, vcc, 0, v83, vcc
	global_load_ushort v195, v[212:213], off offset:320
	v_add_co_u32_e32 v214, vcc, 0x5000, v82
	s_nop 1
	v_addc_co_u32_e32 v215, vcc, 0, v83, vcc
	global_load_ushort v198, v[214:215], off offset:640
	v_add_co_u32_e32 v212, vcc, s23, v82
	s_nop 1
	v_addc_co_u32_e32 v213, vcc, 0, v83, vcc
	global_load_ushort v199, v[212:213], off offset:1088
	v_add_co_u32_e32 v214, vcc, s24, v82
	s_nop 1
	v_addc_co_u32_e32 v215, vcc, 0, v83, vcc
	global_load_ushort v200, v[214:215], off offset:1408
	v_add_co_u32_e32 v212, vcc, s25, v82
	s_nop 1
	v_addc_co_u32_e32 v213, vcc, 0, v83, vcc
	global_load_ushort v201, v[212:213], off offset:1728
	v_add_co_u32_e32 v214, vcc, s21, v82
	s_nop 1
	v_addc_co_u32_e32 v215, vcc, 0, v83, vcc
	global_load_ushort v202, v[214:215], off offset:2048
	v_add_co_u32_e32 v212, vcc, 0x49000, v82
	s_nop 1
	v_addc_co_u32_e32 v213, vcc, 0, v83, vcc
	global_load_ushort v203, v[212:213], off offset:3008
	v_add_co_u32_e32 v214, vcc, 0x4b000, v82
	s_nop 1
	v_addc_co_u32_e32 v215, vcc, 0, v83, vcc
	global_load_ushort v204, v[214:215], off offset:3328
	v_add_co_u32_e32 v212, vcc, 0x4d000, v82
	s_nop 1
	v_addc_co_u32_e32 v213, vcc, 0, v83, vcc
	global_load_ushort v205, v[212:213], off offset:3648
	v_add_co_u32_e32 v214, vcc, 0x4f000, v82
	s_nop 1
	v_addc_co_u32_e32 v215, vcc, 0, v83, vcc
	global_load_ushort v206, v[214:215], off offset:3968
	v_add_co_u32_e32 v212, vcc, 0x52000, v82
	s_nop 1
	v_addc_co_u32_e32 v213, vcc, 0, v83, vcc
	global_load_ushort v207, v[212:213], off offset:192
	v_add_co_u32_e32 v214, vcc, 0x45000, v82
	s_nop 1
	v_addc_co_u32_e32 v215, vcc, 0, v83, vcc
	global_load_ushort v208, v[214:215], off offset:2368
	v_add_co_u32_e32 v212, vcc, 0x47000, v82
	s_nop 1
	v_addc_co_u32_e32 v213, vcc, 0, v83, vcc
	global_load_ushort v209, v[212:213], off offset:2688
	s_movk_i32 s16, 0x7000
	s_nop 0
	global_load_dword v122, v[80:81], off
	global_load_dword v123, v[80:81], off offset:64
	global_load_dword v96, v[80:81], off offset:128
	global_load_dword v97, v[80:81], off offset:192
	global_load_dword v86, v[80:81], off offset:256
	global_load_dword v87, v[80:81], off offset:320
	global_load_dword v84, v[80:81], off offset:384
	global_load_dword v85, v[80:81], off offset:448
	s_mov_b32 s16, 0x9000
	s_waitcnt vmcnt(27)
	v_lshlrev_b32_e32 v127, 16, v218
	v_lshlrev_b32_e32 v101, 16, v217
	v_lshlrev_b32_e32 v100, 16, v216
	v_mov_b32_e32 v126, v101
	v_pk_fma_f32 v[100:101], v[70:71], v[100:101], v[68:69]
	s_add_u32 s70, s70, 0x85000
	v_pk_fma_f32 v[100:101], v[72:73], v[126:127], v[100:101]
	s_addc_u32 s71, s71, 0
	v_add_u32_e32 v78, 64, v78
	s_cmp_eq_u32 s70, 0x10a000
	s_waitcnt vmcnt(26)
	v_lshlrev_b32_e32 v125, 16, v189
	s_mov_b32 s16, 0xd000
	s_nop 0
	s_nop 0
	s_mov_b32 s16, 0xf000
	s_nop 0
	v_mov_b32_e32 v130, v125
	s_waitcnt vmcnt(25)
	v_lshlrev_b32_e32 v88, 16, v190
	s_waitcnt vmcnt(24)
	v_lshlrev_b32_e32 v89, 16, v191
	v_mov_b32_e32 v90, v89
	s_waitcnt vmcnt(23)
	v_lshlrev_b32_e32 v91, 16, v192
	s_movk_i32 s16, 0x3000
	s_nop 0
	s_movk_i32 s16, 0x5000
	s_nop 0
	v_mov_b32_e32 v94, v91
	s_waitcnt vmcnt(22)
	v_lshlrev_b32_e32 v95, 16, v193
	s_waitcnt vmcnt(21)
	v_lshlrev_b32_e32 v93, 16, v194
	v_mov_b32_e32 v92, v95
	s_waitcnt vmcnt(20)
	v_lshlrev_b32_e32 v128, 16, v195
	v_mov_b32_e32 v131, v128
	s_waitcnt vmcnt(19)
	v_lshlrev_b32_e32 v129, 16, v198
	v_mov_b32_e32 v124, v127
	v_pk_fma_f32 v[100:101], v[74:75], v[124:125], v[100:101]
	v_pk_fma_f32 v[124:125], v[70:71], v[124:125], v[68:69]
	v_pk_fma_f32 v[100:101], v[76:77], v[130:131], v[100:101]
	v_pk_fma_f32 v[124:125], v[72:73], v[130:131], v[124:125]
	v_mul_f32_e32 v79, 0xbfb8aa3b, v100
	v_exp_f32_e32 v126, v79
	v_mul_f32_e32 v79, 0xbfb8aa3b, v101
	v_exp_f32_e32 v127, v79
	v_pk_fma_f32 v[124:125], v[74:75], v[128:129], v[124:125]
	v_pk_add_f32 v[126:127], v[126:127], 1.0 op_sel_hi:[1,0]
	s_nop 0
	v_div_scale_f32 v79, s[16:17], v127, v127, v101
	v_rcp_f32_e32 v160, v79
	s_nop 0
	v_fma_f32 v161, -v79, v160, 1.0
	v_fmac_f32_e32 v160, v161, v160
	v_div_scale_f32 v161, vcc, v101, v127, v101
	v_mul_f32_e32 v162, v161, v160
	v_fma_f32 v163, -v79, v162, v161
	v_fmac_f32_e32 v162, v163, v160
	v_fma_f32 v79, -v79, v162, v161
	v_div_fmas_f32 v79, v79, v160, v162
	v_div_fixup_f32 v101, v79, v127, v101
	v_div_scale_f32 v79, s[16:17], v126, v126, v100
	v_rcp_f32_e32 v127, v79
	s_nop 0
	v_fma_f32 v160, -v79, v127, 1.0
	v_fmac_f32_e32 v127, v160, v127
	v_div_scale_f32 v160, vcc, v100, v126, v100
	v_mul_f32_e32 v161, v160, v127
	v_fma_f32 v162, -v79, v161, v160
	v_fmac_f32_e32 v161, v162, v127
	v_fma_f32 v79, -v79, v161, v160
	v_div_fmas_f32 v79, v79, v127, v161
	v_pk_mov_b32 v[160:161], v[128:129], v[88:89] op_sel:[1,0]
	v_div_fixup_f32 v100, v79, v126, v100
	v_pk_fma_f32 v[124:125], v[76:77], v[160:161], v[124:125]
	v_pk_fma_f32 v[126:127], v[70:71], v[128:129], v[68:69]
	v_mul_f32_e32 v79, 0xbfb8aa3b, v124
	v_exp_f32_e32 v128, v79
	v_mul_f32_e32 v79, 0xbfb8aa3b, v125
	v_exp_f32_e32 v129, v79
	v_pk_fma_f32 v[126:127], v[72:73], v[160:161], v[126:127]
	s_waitcnt vmcnt(6)
	v_pk_mul_f32 v[122:123], v[122:123], v[100:101]
	v_pk_fma_f32 v[126:127], v[74:75], v[88:89], v[126:127]
	v_pk_add_f32 v[128:129], v[128:129], 1.0 op_sel_hi:[1,0]
	v_pk_fma_f32 v[126:127], v[76:77], v[90:91], v[126:127]
	v_div_scale_f32 v79, s[16:17], v129, v129, v125
	v_rcp_f32_e32 v130, v79
	v_pk_fma_f32 v[88:89], v[70:71], v[88:89], v[68:69]
	v_fma_f32 v131, -v79, v130, 1.0
	v_fmac_f32_e32 v130, v131, v130
	v_div_scale_f32 v131, vcc, v125, v129, v125
	v_mul_f32_e32 v162, v131, v130
	v_fma_f32 v163, -v79, v162, v131
	v_fmac_f32_e32 v162, v163, v130
	v_fma_f32 v79, -v79, v162, v131
	v_div_fmas_f32 v79, v79, v130, v162
	v_div_fixup_f32 v125, v79, v129, v125
	v_div_scale_f32 v79, s[16:17], v128, v128, v124
	v_rcp_f32_e32 v129, v79
	v_pk_fma_f32 v[88:89], v[72:73], v[90:91], v[88:89]
	v_fma_f32 v130, -v79, v129, 1.0
	v_fmac_f32_e32 v129, v130, v129
	v_div_scale_f32 v130, vcc, v124, v128, v124
	v_mul_f32_e32 v131, v130, v129
	v_fma_f32 v162, -v79, v131, v130
	v_fmac_f32_e32 v131, v162, v129
	v_fma_f32 v79, -v79, v131, v130
	v_div_fmas_f32 v79, v79, v129, v131
	v_div_fixup_f32 v124, v79, v128, v124
	v_mul_f32_e32 v79, 0xbfb8aa3b, v126
	v_exp_f32_e32 v128, v79
	v_mul_f32_e32 v79, 0xbfb8aa3b, v127
	v_exp_f32_e32 v129, v79
	v_pk_fma_f32 v[88:89], v[74:75], v[94:95], v[88:89]
	s_waitcnt vmcnt(4)
	v_pk_mul_f32 v[96:97], v[96:97], v[124:125]
	v_pk_fma_f32 v[88:89], v[76:77], v[92:93], v[88:89]
	v_pk_add_f32 v[128:129], v[128:129], 1.0 op_sel_hi:[1,0]
	s_nop 0
	v_div_scale_f32 v79, s[16:17], v129, v129, v127
	v_rcp_f32_e32 v130, v79
	s_nop 0
	v_fma_f32 v131, -v79, v130, 1.0
	v_fmac_f32_e32 v130, v131, v130
	v_div_scale_f32 v131, vcc, v127, v129, v127
	v_mul_f32_e32 v160, v131, v130
	v_fma_f32 v161, -v79, v160, v131
	v_fmac_f32_e32 v160, v161, v130
	v_fma_f32 v79, -v79, v160, v131
	v_div_fmas_f32 v79, v79, v130, v160
	v_div_fixup_f32 v127, v79, v129, v127
	v_div_scale_f32 v79, s[16:17], v128, v128, v126
	v_rcp_f32_e32 v129, v79
	s_nop 0
	v_fma_f32 v130, -v79, v129, 1.0
	v_fmac_f32_e32 v129, v130, v129
	v_div_scale_f32 v130, vcc, v126, v128, v126
	v_mul_f32_e32 v131, v130, v129
	v_fma_f32 v160, -v79, v131, v130
	v_fmac_f32_e32 v131, v160, v129
	v_fma_f32 v79, -v79, v131, v130
	v_div_fmas_f32 v79, v79, v129, v131
	v_div_fixup_f32 v126, v79, v128, v126
	v_mul_f32_e32 v79, 0xbfb8aa3b, v88
	v_exp_f32_e32 v90, v79
	v_mul_f32_e32 v79, 0xbfb8aa3b, v89
	v_exp_f32_e32 v91, v79
	s_waitcnt vmcnt(2)
	v_pk_mul_f32 v[86:87], v[86:87], v[126:127]
	v_pk_add_f32 v[90:91], v[90:91], 1.0 op_sel_hi:[1,0]
	s_nop 0
	v_div_scale_f32 v79, s[16:17], v91, v91, v89
	v_rcp_f32_e32 v92, v79
	v_cvt_pk_bf16_f32 v86, v86, v87
	v_fma_f32 v93, -v79, v92, 1.0
	v_fmac_f32_e32 v92, v93, v92
	v_div_scale_f32 v93, vcc, v89, v91, v89
	v_mul_f32_e32 v94, v93, v92
	v_fma_f32 v95, -v79, v94, v93
	v_fmac_f32_e32 v94, v95, v92
	v_fma_f32 v79, -v79, v94, v93
	v_div_fmas_f32 v79, v79, v92, v94
	v_div_fixup_f32 v89, v79, v91, v89
	v_div_scale_f32 v79, s[16:17], v90, v90, v88
	v_rcp_f32_e32 v91, v79
	s_mov_b32 s16, 0x49000
	v_fma_f32 v92, -v79, v91, 1.0
	v_fmac_f32_e32 v91, v92, v91
	v_div_scale_f32 v92, vcc, v88, v90, v88
	v_mul_f32_e32 v93, v92, v91
	v_fma_f32 v94, -v79, v93, v92
	v_fmac_f32_e32 v93, v94, v91
	v_fma_f32 v79, -v79, v93, v92
	v_div_fmas_f32 v79, v79, v91, v93
	v_div_fixup_f32 v88, v79, v90, v88
	s_waitcnt vmcnt(0)
	v_pk_mul_f32 v[90:91], v[84:85], v[88:89]
	v_cvt_pk_bf16_f32 v84, v122, v123
	v_cvt_pk_bf16_f32 v85, v96, v97
	v_cvt_pk_bf16_f32 v87, v90, v91
	ds_write_b128 v99, v[84:87]
	v_cvt_pk_bf16_f32 v84, v100, v101
	v_cvt_pk_bf16_f32 v85, v124, v125
	v_cvt_pk_bf16_f32 v86, v126, v127
	v_cvt_pk_bf16_f32 v87, v88, v89
	ds_write_b128 v99, v[84:87] offset:17408
	s_nop 1
	v_lshlrev_b32_e32 v124, 16, v199
	v_lshlrev_b32_e32 v125, 16, v200
	v_mov_b32_e32 v126, v125
	s_nop 0
	s_mov_b32 s16, 0x4b000
	s_nop 0
	v_lshlrev_b32_e32 v127, 16, v201
	global_load_dword v122, v[80:81], off offset:2048
	global_load_dword v123, v[80:81], off offset:2112
	global_load_dword v96, v[80:81], off offset:2176
	global_load_dword v97, v[80:81], off offset:2240
	global_load_dword v86, v[80:81], off offset:2304
	global_load_dword v87, v[80:81], off offset:2368
	global_load_dword v84, v[80:81], off offset:2432
	global_load_dword v85, v[80:81], off offset:2496
	v_mov_b32_e32 v100, v127
	v_lshl_add_u64 v[80:81], v[80:81], 0, s[60:61]
	v_lshlrev_b32_e32 v101, 16, v202
	s_mov_b32 s16, 0x4d000
	s_nop 0
	s_nop 0
	s_mov_b32 s16, 0x4f000
	s_mov_b32 s16, 0x52000
	s_nop 0
	v_lshlrev_b32_e32 v88, 16, v203
	v_lshlrev_b32_e32 v89, 16, v204
	v_mov_b32_e32 v90, v89
	v_lshlrev_b32_e32 v91, 16, v205
	s_mov_b32 s16, 0x45000
	s_nop 0
	s_mov_b32 s16, 0x47000
	s_nop 0
	s_nop 0
	v_mov_b32_e32 v94, v91
	v_lshlrev_b32_e32 v95, 16, v206
	v_lshlrev_b32_e32 v128, 16, v208
	v_lshlrev_b32_e32 v93, 16, v207
	v_mov_b32_e32 v92, v95
	v_lshlrev_b32_e32 v129, 16, v209
	v_pk_fma_f32 v[82:83], v[70:71], v[124:125], v[68:69]
	v_mov_b32_e32 v124, v101
	v_pk_fma_f32 v[82:83], v[72:73], v[126:127], v[82:83]
	v_mov_b32_e32 v125, v128
	v_pk_fma_f32 v[82:83], v[74:75], v[100:101], v[82:83]
	v_pk_fma_f32 v[100:101], v[70:71], v[100:101], v[68:69]
	v_pk_fma_f32 v[82:83], v[76:77], v[124:125], v[82:83]
	v_pk_fma_f32 v[100:101], v[72:73], v[124:125], v[100:101]
	v_mul_f32_e32 v79, 0xbfb8aa3b, v82
	v_exp_f32_e32 v126, v79
	v_mul_f32_e32 v79, 0xbfb8aa3b, v83
	v_exp_f32_e32 v127, v79
	v_pk_fma_f32 v[100:101], v[74:75], v[128:129], v[100:101]
	v_pk_add_f32 v[126:127], v[126:127], 1.0 op_sel_hi:[1,0]
	s_nop 0
	v_div_scale_f32 v79, s[16:17], v127, v127, v83
	v_rcp_f32_e32 v130, v79
	s_nop 0
	v_fma_f32 v131, -v79, v130, 1.0
	v_fmac_f32_e32 v130, v131, v130
	v_div_scale_f32 v131, vcc, v83, v127, v83
	v_mul_f32_e32 v160, v131, v130
	v_fma_f32 v161, -v79, v160, v131
	v_fmac_f32_e32 v160, v161, v130
	v_fma_f32 v79, -v79, v160, v131
	v_div_fmas_f32 v79, v79, v130, v160
	v_div_fixup_f32 v83, v79, v127, v83
	v_div_scale_f32 v79, s[16:17], v126, v126, v82
	v_rcp_f32_e32 v127, v79
	s_nop 0
	v_fma_f32 v130, -v79, v127, 1.0
	v_fmac_f32_e32 v127, v130, v127
	v_div_scale_f32 v130, vcc, v82, v126, v82
	v_mul_f32_e32 v131, v130, v127
	v_fma_f32 v160, -v79, v131, v130
	v_fmac_f32_e32 v131, v160, v127
	v_fma_f32 v79, -v79, v131, v130
	v_div_fmas_f32 v79, v79, v127, v131
	v_pk_mov_b32 v[130:131], v[128:129], v[88:89] op_sel:[1,0]
	v_div_fixup_f32 v82, v79, v126, v82
	v_pk_fma_f32 v[100:101], v[76:77], v[130:131], v[100:101]
	v_pk_fma_f32 v[126:127], v[70:71], v[128:129], v[68:69]
	v_mul_f32_e32 v79, 0xbfb8aa3b, v100
	v_exp_f32_e32 v124, v79
	v_mul_f32_e32 v79, 0xbfb8aa3b, v101
	v_exp_f32_e32 v125, v79
	s_waitcnt vmcnt(6)
	v_pk_mul_f32 v[122:123], v[122:123], v[82:83]
	v_cvt_pk_bf16_f32 v82, v82, v83
	v_pk_add_f32 v[124:125], v[124:125], 1.0 op_sel_hi:[1,0]
	s_nop 0
	v_div_scale_f32 v79, s[16:17], v125, v125, v101
	v_rcp_f32_e32 v128, v79
	s_nop 0
	v_fma_f32 v129, -v79, v128, 1.0
	v_fmac_f32_e32 v128, v129, v128
	v_div_scale_f32 v129, vcc, v101, v125, v101
	v_mul_f32_e32 v160, v129, v128
	v_fma_f32 v161, -v79, v160, v129
	v_fmac_f32_e32 v160, v161, v128
	v_fma_f32 v79, -v79, v160, v129
	v_div_fmas_f32 v79, v79, v128, v160
	v_div_fixup_f32 v101, v79, v125, v101
	v_div_scale_f32 v79, s[16:17], v124, v124, v100
	v_rcp_f32_e32 v125, v79
	s_nop 0
	v_fma_f32 v128, -v79, v125, 1.0
	v_fmac_f32_e32 v125, v128, v125
	v_div_scale_f32 v128, vcc, v100, v124, v100
	v_mul_f32_e32 v129, v128, v125
	v_fma_f32 v160, -v79, v129, v128
	v_fmac_f32_e32 v129, v160, v125
	v_fma_f32 v79, -v79, v129, v128
	v_div_fmas_f32 v79, v79, v125, v129
	v_div_fixup_f32 v100, v79, v124, v100
	v_pk_fma_f32 v[124:125], v[72:73], v[130:131], v[126:127]
	s_waitcnt vmcnt(4)
	v_pk_mul_f32 v[96:97], v[96:97], v[100:101]
	v_pk_fma_f32 v[124:125], v[74:75], v[88:89], v[124:125]
	v_pk_fma_f32 v[88:89], v[70:71], v[88:89], v[68:69]
	v_pk_fma_f32 v[124:125], v[76:77], v[90:91], v[124:125]
	v_pk_fma_f32 v[88:89], v[72:73], v[90:91], v[88:89]
	v_mul_f32_e32 v79, 0xbfb8aa3b, v124
	v_exp_f32_e32 v126, v79
	v_mul_f32_e32 v79, 0xbfb8aa3b, v125
	v_exp_f32_e32 v127, v79
	v_pk_fma_f32 v[88:89], v[74:75], v[94:95], v[88:89]
	v_cvt_pk_bf16_f32 v83, v100, v101
	v_pk_fma_f32 v[88:89], v[76:77], v[92:93], v[88:89]
	v_pk_add_f32 v[126:127], v[126:127], 1.0 op_sel_hi:[1,0]
	s_nop 0
	v_div_scale_f32 v79, s[16:17], v127, v127, v125
	v_rcp_f32_e32 v128, v79
	s_nop 0
	v_fma_f32 v129, -v79, v128, 1.0
	v_fmac_f32_e32 v128, v129, v128
	v_div_scale_f32 v129, vcc, v125, v127, v125
	v_mul_f32_e32 v130, v129, v128
	v_fma_f32 v131, -v79, v130, v129
	v_fmac_f32_e32 v130, v131, v128
	v_fma_f32 v79, -v79, v130, v129
	v_div_fmas_f32 v79, v79, v128, v130
	v_div_fixup_f32 v125, v79, v127, v125
	v_div_scale_f32 v79, s[16:17], v126, v126, v124
	v_rcp_f32_e32 v127, v79
	s_nop 0
	v_fma_f32 v128, -v79, v127, 1.0
	v_fmac_f32_e32 v127, v128, v127
	v_div_scale_f32 v128, vcc, v124, v126, v124
	v_mul_f32_e32 v129, v128, v127
	v_fma_f32 v130, -v79, v129, v128
	v_fmac_f32_e32 v129, v130, v127
	v_fma_f32 v79, -v79, v129, v128
	v_div_fmas_f32 v79, v79, v127, v129
	v_div_fixup_f32 v124, v79, v126, v124
	v_mul_f32_e32 v79, 0xbfb8aa3b, v88
	v_exp_f32_e32 v90, v79
	v_mul_f32_e32 v79, 0xbfb8aa3b, v89
	v_exp_f32_e32 v91, v79
	s_waitcnt vmcnt(2)
	v_pk_mul_f32 v[86:87], v[86:87], v[124:125]
	v_pk_add_f32 v[90:91], v[90:91], 1.0 op_sel_hi:[1,0]
	s_nop 0
	v_div_scale_f32 v79, s[16:17], v91, v91, v89
	v_rcp_f32_e32 v92, v79
	v_cvt_pk_bf16_f32 v86, v86, v87
	v_fma_f32 v93, -v79, v92, 1.0
	v_fmac_f32_e32 v92, v93, v92
	v_div_scale_f32 v93, vcc, v89, v91, v89
	v_mul_f32_e32 v94, v93, v92
	v_fma_f32 v95, -v79, v94, v93
	v_fmac_f32_e32 v94, v95, v92
	v_fma_f32 v79, -v79, v94, v93
	v_div_fmas_f32 v79, v79, v92, v94
	v_div_fixup_f32 v89, v79, v91, v89
	v_div_scale_f32 v79, s[16:17], v90, v90, v88
	v_rcp_f32_e32 v91, v79
	s_nop 0
	v_fma_f32 v92, -v79, v91, 1.0
	v_fmac_f32_e32 v91, v92, v91
	v_div_scale_f32 v92, vcc, v88, v90, v88
	v_mul_f32_e32 v93, v92, v91
	v_fma_f32 v94, -v79, v93, v92
	v_fmac_f32_e32 v93, v94, v91
	v_fma_f32 v79, -v79, v93, v92
	v_div_fmas_f32 v79, v79, v91, v93
	v_div_fixup_f32 v88, v79, v90, v88
	s_waitcnt vmcnt(0)
	v_pk_mul_f32 v[90:91], v[84:85], v[88:89]
	v_cvt_pk_bf16_f32 v84, v122, v123
	v_cvt_pk_bf16_f32 v85, v96, v97
	v_cvt_pk_bf16_f32 v87, v90, v91
	ds_write_b128 v99, v[84:87] offset:64
	v_cvt_pk_bf16_f32 v84, v124, v125
	v_cvt_pk_bf16_f32 v85, v88, v89
	ds_write_b128 v99, v[82:85] offset:17472
	v_add_u32_e32 v99, 0x80, v99
	s_cbranch_scc1 .LBB0_594

.LBB0_572:
	s_or_b64 exec, exec, s[62:63]
	v_mov_b32_e32 v216, 0
	s_and_saveexec_b64 s[16:17], s[66:67]
	s_cbranch_execz .LBB0_574
.LBB0_573:
	v_lshl_add_u64 v[82:83], v[66:67], 1, v[82:83]
	global_load_ushort v216, v[82:83], off

.LBB0_576:
	s_or_b64 exec, exec, s[62:63]
	v_mov_b32_e32 v217, 0
	s_and_saveexec_b64 s[16:17], s[66:67]
	s_cbranch_execz .LBB0_578
.LBB0_577:
	v_lshl_add_u64 v[82:83], v[66:67], 1, v[82:83]
	global_load_ushort v217, v[82:83], off

.LBB0_580:
	s_or_b64 exec, exec, s[62:63]
	v_mov_b32_e32 v218, 0
	s_and_saveexec_b64 s[16:17], s[66:67]
	s_cbranch_execz .LBB0_569
	s_branch .LBB0_593

.LBB0_584:
	s_or_b64 exec, exec, s[16:17]
	s_andn2_b64 s[16:17], s[66:67], exec
	s_and_b64 s[18:19], s[68:69], exec
	s_or_b64 s[66:67], s[16:17], s[18:19]
	s_or_b64 exec, exec, s[62:63]
	v_mov_b32_e32 v216, 0
	s_and_saveexec_b64 s[16:17], s[66:67]
	s_cbranch_execnz .LBB0_573
	s_branch .LBB0_574

.LBB0_588:
	s_or_b64 exec, exec, s[16:17]
	s_andn2_b64 s[16:17], s[66:67], exec
	s_and_b64 s[18:19], s[68:69], exec
	s_or_b64 s[66:67], s[16:17], s[18:19]
	s_or_b64 exec, exec, s[62:63]
	v_mov_b32_e32 v217, 0
	s_and_saveexec_b64 s[16:17], s[66:67]
	s_cbranch_execnz .LBB0_577
	s_branch .LBB0_578

.LBB0_592:
	s_or_b64 exec, exec, s[16:17]
	s_andn2_b64 s[16:17], s[66:67], exec
	s_and_b64 s[18:19], s[68:69], exec
	s_or_b64 s[66:67], s[16:17], s[18:19]
	s_or_b64 exec, exec, s[62:63]
	v_mov_b32_e32 v218, 0
	s_and_saveexec_b64 s[16:17], s[66:67]
	s_cbranch_execz .LBB0_569
.LBB0_593:
	v_lshl_add_u64 v[82:83], v[66:67], 1, v[82:83]
	global_load_ushort v218, v[82:83], off
	s_branch .LBB0_569
